# accumulator zeroing per GEMM tile by 8 MFMA (0*0+0) instead of 128 v_mov, and wout0's stray vmcnt(0) before the K-loop removed
# speedup vs baseline: 1.0149x; 1.0009x over previous
; template <class Get, class Epi>
; DI void gemm_stream(LAS unsigned char* lds, const int K, const int ld, Get get, Epi epi) {
;     ...
;         ZERO_ACC;
;         cur = nxt; cA = nA; cB = nB; ++ui;
.LBB0_725:
	s_add_u32 s4, s4, 0x80080
	s_addc_u32 s5, s5, 0
	s_add_u32 s29, s6, 0x100
	s_addc_u32 s55, s7, 0
	s_mov_b32 vcc_lo, -2
	v_mov_b32_e32 v128, 0
	v_mov_b32_e32 v129, 0
	v_mov_b32_e32 v130, 0
	v_mov_b32_e32 v131, 0
	s_nop 1
	v_mfma_f32_32x32x16_bf16 v[0:15], v[128:131], v[128:131], 0
	v_mfma_f32_32x32x16_bf16 v[16:31], v[128:131], v[128:131], 0
	v_mfma_f32_32x32x16_bf16 v[32:47], v[128:131], v[128:131], 0
	v_mfma_f32_32x32x16_bf16 v[48:63], v[128:131], v[128:131], 0
	v_mfma_f32_32x32x16_bf16 v[64:79], v[128:131], v[128:131], 0
	v_mfma_f32_32x32x16_bf16 v[80:95], v[128:131], v[128:131], 0
	v_mfma_f32_32x32x16_bf16 v[96:111], v[128:131], v[128:131], 0
	v_mfma_f32_32x32x16_bf16 v[112:127], v[128:131], v[128:131], 0

; template <class Get, class Epi>
; DI void gemm_stream(LAS unsigned char* lds, const int K, const int ld, Get get, Epi epi) {
;     ...
;         ZERO_ACC;
;         cur = nxt; cA = nA; cB = nB; ++ui;
.LBB0_1237:
	s_add_u32 s16, s8, 0x100
	s_addc_u32 s17, s9, 0
	s_mov_b32 s18, -2
	v_mov_b32_e32 v128, 0
	v_mov_b32_e32 v129, 0
	v_mov_b32_e32 v130, 0
	v_mov_b32_e32 v131, 0
	s_nop 1
	v_mfma_f32_32x32x16_bf16 v[0:15], v[128:131], v[128:131], 0
	v_mfma_f32_32x32x16_bf16 v[16:31], v[128:131], v[128:131], 0
	v_mfma_f32_32x32x16_bf16 v[32:47], v[128:131], v[128:131], 0
	v_mfma_f32_32x32x16_bf16 v[48:63], v[128:131], v[128:131], 0
	v_mfma_f32_32x32x16_bf16 v[64:79], v[128:131], v[128:131], 0
	v_mfma_f32_32x32x16_bf16 v[80:95], v[128:131], v[128:131], 0
	v_mfma_f32_32x32x16_bf16 v[96:111], v[128:131], v[128:131], 0
	v_mfma_f32_32x32x16_bf16 v[112:127], v[128:131], v[128:131], 0

; template <class Get, class Epi>
; DI void gemm_stream(LAS unsigned char* lds, const int K, const int ld, Get get, Epi epi) {
;     ...
;         ZERO_ACC;
;         cur = nxt; cA = nA; cB = nB; ++ui;
.LBB0_1629:
	s_add_u32 s10, s10, 0x80080
	s_addc_u32 s11, s11, 0
	s_add_u32 s57, s12, 0x100
	s_addc_u32 s58, s13, 0
	s_mov_b32 s59, -2
	v_mov_b32_e32 v148, 0
	v_mov_b32_e32 v149, 0
	v_mov_b32_e32 v150, 0
	v_mov_b32_e32 v151, 0
	s_nop 1
	v_mfma_f32_32x32x16_bf16 v[0:15], v[148:151], v[148:151], 0
	v_mfma_f32_32x32x16_bf16 v[16:31], v[148:151], v[148:151], 0
	v_mfma_f32_32x32x16_bf16 v[32:47], v[148:151], v[148:151], 0
	v_mfma_f32_32x32x16_bf16 v[48:63], v[148:151], v[148:151], 0
	v_mfma_f32_32x32x16_bf16 v[64:79], v[148:151], v[148:151], 0
	v_mfma_f32_32x32x16_bf16 v[80:95], v[148:151], v[148:151], 0
	v_mfma_f32_32x32x16_bf16 v[96:111], v[148:151], v[148:151], 0
	v_mfma_f32_32x32x16_bf16 v[112:127], v[148:151], v[148:151], 0

; template <class Get, class Epi>
; DI void gemm_stream(LAS unsigned char* lds, const int K, const int ld, Get get, Epi epi) {
;     ...
;         ZERO_ACC;
;         cur = nxt; cA = nA; cB = nB; ++ui;
.LBB0_1696:
	s_add_u32 s14, s8, 0x100
	s_addc_u32 s15, s9, 0
	s_mov_b32 s16, -2
	v_mov_b32_e32 v128, 0
	v_mov_b32_e32 v129, 0
	v_mov_b32_e32 v130, 0
	v_mov_b32_e32 v131, 0
	s_nop 1
	v_mfma_f32_32x32x16_bf16 v[0:15], v[128:131], v[128:131], 0
	v_mfma_f32_32x32x16_bf16 v[16:31], v[128:131], v[128:131], 0
	v_mfma_f32_32x32x16_bf16 v[32:47], v[128:131], v[128:131], 0
	v_mfma_f32_32x32x16_bf16 v[48:63], v[128:131], v[128:131], 0
	v_mfma_f32_32x32x16_bf16 v[64:79], v[128:131], v[128:131], 0
	v_mfma_f32_32x32x16_bf16 v[80:95], v[128:131], v[128:131], 0
	v_mfma_f32_32x32x16_bf16 v[96:111], v[128:131], v[128:131], 0
	v_mfma_f32_32x32x16_bf16 v[112:127], v[128:131], v[128:131], 0

; template <class Get, class Epi>
; DI void gemm_stream(LAS unsigned char* lds, const int K, const int ld, Get get, Epi epi) {
;     ...
;         ZERO_ACC;
;         cur = nxt; cA = nA; cB = nB; ++ui;
.LBB0_1963:
	s_add_u32 s0, s38, 0x100
	s_addc_u32 s76, s39, 0
	s_mov_b32 s77, -2
	v_mov_b32_e32 v144, 0
	v_mov_b32_e32 v145, 0
	v_mov_b32_e32 v146, 0
	v_mov_b32_e32 v147, 0
	s_nop 1
	v_mfma_f32_32x32x16_bf16 v[0:15], v[144:147], v[144:147], 0
	v_mfma_f32_32x32x16_bf16 v[16:31], v[144:147], v[144:147], 0
	v_mfma_f32_32x32x16_bf16 v[32:47], v[144:147], v[144:147], 0
	v_mfma_f32_32x32x16_bf16 v[48:63], v[144:147], v[144:147], 0
	v_mfma_f32_32x32x16_bf16 v[64:79], v[144:147], v[144:147], 0
	v_mfma_f32_32x32x16_bf16 v[80:95], v[144:147], v[144:147], 0
	v_mfma_f32_32x32x16_bf16 v[96:111], v[144:147], v[144:147], 0
	v_mfma_f32_32x32x16_bf16 v[112:127], v[144:147], v[144:147], 0

; template <class Get, class Epi>
; DI void gemm_stream(LAS unsigned char* lds, const int K, const int ld, Get get, Epi epi) {
;     ...
;         ZERO_ACC;
;         cur = nxt; cA = nA; cB = nB; ++ui;
.LBB0_2101:
	s_add_u32 s64, s64, 0x80080
	s_addc_u32 s65, s65, 0
	s_add_u32 s2, s74, 0x100
	s_addc_u32 s3, s75, 0
	s_mov_b32 s7, -2
	v_mov_b32_e32 v128, 0
	v_mov_b32_e32 v129, 0
	v_mov_b32_e32 v130, 0
	v_mov_b32_e32 v131, 0
	s_nop 1
	v_mfma_f32_32x32x16_bf16 v[0:15], v[128:131], v[128:131], 0
	v_mfma_f32_32x32x16_bf16 v[16:31], v[128:131], v[128:131], 0
	v_mfma_f32_32x32x16_bf16 v[32:47], v[128:131], v[128:131], 0
	v_mfma_f32_32x32x16_bf16 v[48:63], v[128:131], v[128:131], 0
	v_mfma_f32_32x32x16_bf16 v[64:79], v[128:131], v[128:131], 0
	v_mfma_f32_32x32x16_bf16 v[80:95], v[128:131], v[128:131], 0
	v_mfma_f32_32x32x16_bf16 v[96:111], v[128:131], v[128:131], 0
	v_mfma_f32_32x32x16_bf16 v[112:127], v[128:131], v[128:131], 0

; template <class Get, class Epi>
; DI void gemm_stream(LAS unsigned char* lds, const int K, const int ld, Get get, Epi epi) {
;     ...
;         ZERO_ACC;
;         cur = nxt; cA = nA; cB = nB; ++ui;
.LBB0_3045:
	s_add_u32 s12, s12, 0x80080
	s_addc_u32 s13, s13, 0
	s_add_u32 s0, s14, 0x100
	s_addc_u32 s55, s15, 0
	s_mov_b32 s56, -2
	v_mov_b32_e32 v148, 0
	v_mov_b32_e32 v149, 0
	v_mov_b32_e32 v150, 0
	v_mov_b32_e32 v151, 0
	s_nop 1
	v_mfma_f32_32x32x16_bf16 v[0:15], v[148:151], v[148:151], 0
	v_mfma_f32_32x32x16_bf16 v[16:31], v[148:151], v[148:151], 0
	v_mfma_f32_32x32x16_bf16 v[32:47], v[148:151], v[148:151], 0
	v_mfma_f32_32x32x16_bf16 v[48:63], v[148:151], v[148:151], 0
	v_mfma_f32_32x32x16_bf16 v[64:79], v[148:151], v[148:151], 0
	v_mfma_f32_32x32x16_bf16 v[80:95], v[148:151], v[148:151], 0
	v_mfma_f32_32x32x16_bf16 v[96:111], v[148:151], v[148:151], 0
	v_mfma_f32_32x32x16_bf16 v[112:127], v[148:151], v[148:151], 0

; template <class Get, class Epi>
; DI void gemm_stream(LAS unsigned char* lds, const int K, const int ld, Get get, Epi epi) {
;     ...
;         ZERO_ACC;
;         cur = nxt; cA = nA; cB = nB; ++ui;
.LBB0_3112:
	s_add_u32 s14, s6, 0x100
	s_addc_u32 s15, s7, 0
	s_mov_b32 s16, -2
	v_mov_b32_e32 v128, 0
	v_mov_b32_e32 v129, 0
	v_mov_b32_e32 v130, 0
	v_mov_b32_e32 v131, 0
	s_nop 1
	v_mfma_f32_32x32x16_bf16 v[0:15], v[128:131], v[128:131], 0
	v_mfma_f32_32x32x16_bf16 v[16:31], v[128:131], v[128:131], 0
	v_mfma_f32_32x32x16_bf16 v[32:47], v[128:131], v[128:131], 0
	v_mfma_f32_32x32x16_bf16 v[48:63], v[128:131], v[128:131], 0
	v_mfma_f32_32x32x16_bf16 v[64:79], v[128:131], v[128:131], 0
	v_mfma_f32_32x32x16_bf16 v[80:95], v[128:131], v[128:131], 0
	v_mfma_f32_32x32x16_bf16 v[96:111], v[128:131], v[128:131], 0
	v_mfma_f32_32x32x16_bf16 v[112:127], v[128:131], v[128:131], 0
